# local seams simplified: fire-and-forget arrival atomic then poll the arrival counter (no returning atomic, no generation word)
# baseline (speedup 1.0000x reference)
; #define LAS __attribute__((address_space(3)))
; __device__ __forceinline__ unsigned xb_ld(unsigned* p)              { return __hip_atomic_load(p, __ATOMIC_RELAXED, __HIP_MEMORY_SCOPE_AGENT); }
; __device__ __forceinline__ unsigned xb_add(unsigned* p, unsigned v) { return __hip_atomic_fetch_add(p, v, __ATOMIC_RELAXED, __HIP_MEMORY_SCOPE_AGENT); }
; __device__ __forceinline__ unsigned xb_xcc_id() { return (unsigned)__builtin_amdgcn_s_getreg((3 << 11) | 20) & 0xFu; }
; #define XB_SPIN(cond, bar) do { unsigned _sp = 0; while (cond) { __builtin_amdgcn_s_sleep(1); \
;     if ((++_sp & 255u) == 0u) { if (xb_ld(&(bar)[XB_TMO])) break; if (_sp > XB_SPIN_CAP) { atomicAdd(&(bar)[XB_TMO], 1u); break; } } } } while (0)
; __device__ __forceinline__ bool is_leader(int wave_s) { int lane; asm volatile("v_mbcnt_lo_u32_b32 %0, -1, 0\n\tv_mbcnt_hi_u32_b32 %0, -1, %0" : "=v"(lane)); return wave_s == 0 && lane == 0; }
; __device__ __forceinline__ void grid_bar(unsigned* bar, volatile LAS unsigned* st, int wave_s, unsigned G) {
;     asm volatile("s_waitcnt vmcnt(0) lgkmcnt(0)" ::: "memory");
;     __syncthreads();
;     if (is_leader(wave_s)) {
;         const unsigned x = xb_xcc_id();
;         unsigned nloc = st[0], nx = st[1];
;         if (nloc == 0u) { xcd_barrier_complete(bar, x, G, nloc, nx); st[0] = nloc; st[1] = nx; }
;         const unsigned old = xb_add(&bar[XB_XSUB(x)], 1u);
;         const unsigned gen = old / nloc;
;         if (old + 1u == (gen + 1u) * nloc) {
;             __builtin_amdgcn_fence(__ATOMIC_RELEASE, "agent");
;             asm volatile("s_waitcnt vmcnt(0)" ::: "memory");
;             const unsigned og = xb_add(&bar[XB_TOP], 1u);
;             const unsigned tg = og / nx;
;             if (og + 1u == (tg + 1u) * nx) xb_add(&bar[XB_TOPGEN], 1u);
;             else XB_SPIN(xb_ld(&bar[XB_TOPGEN]) == tg, bar);
;             __builtin_amdgcn_fence(__ATOMIC_ACQUIRE, "agent");
;             xb_add(&bar[XB_XGEN(x)], 1u);
;             asm volatile("s_waitcnt vmcnt(0)" ::: "memory");
;         } else {
;             XB_SPIN(xb_ld(&bar[XB_XGEN(x)]) == gen, bar);
;             __builtin_amdgcn_fence(__ATOMIC_ACQUIRE, "agent");
;             asm volatile("s_waitcnt vmcnt(0)" ::: "memory");
;         }
;     }
;     __syncthreads();
; }
.LBB0_272:
	s_mov_b32 s4, s95
	s_mov_b32 s2, s94
	s_cmp_lt_i32 s2, 2
	s_cselect_b64 s[2:3], -1, 0
	s_cmp_gt_i32 s4, 1
	s_cselect_b64 s[4:5], -1, 0
	s_and_b64 s[2:3], s[2:3], s[4:5]
	s_andn2_b64 vcc, exec, s[2:3]
	s_cbranch_vccnz .LBB0_327
	s_mov_b32 s2, s94
	s_mov_b32 s4, s95
	s_cmp_lt_i32 s2, 3
	s_cselect_b64 s[2:3], -1, 0
	s_cmp_gt_i32 s4, 2
	s_cselect_b64 s[4:5], -1, 0
	s_and_b64 s[2:3], s[2:3], s[4:5]
	s_andn2_b64 vcc, exec, s[2:3]
	s_cbranch_vccnz .LBB0_327
	s_cmp_lt_u32 s79, 64
	s_waitcnt vmcnt(0) lgkmcnt(0)
	s_cselect_b64 s[2:3], -1, 0
	s_waitcnt vmcnt(0) lgkmcnt(0)
	s_barrier
	v_mbcnt_lo_u32_b32 v0, -1, 0
	v_mbcnt_hi_u32_b32 v0, -1, v0
	s_nop 0
	v_cmp_eq_u32_e32 vcc, 0, v0
	s_and_b64 s[4:5], s[2:3], vcc
	s_and_saveexec_b64 s[2:3], s[4:5]
	s_cbranch_execz .LBB0_326
	s_cmp_eq_u32 s98, 0
	s_cbranch_scc1 .Lgl_1
	s_load_dwordx2 s[4:5], s[0:1], 0xf0
	s_and_b32 s6, s78, 7
	s_lshl_b32 s6, s6, 8
	s_lshr_b32 s7, s92, 3
	s_mul_i32 s7, s7, 1
	v_mov_b32_e32 v0, s6
	v_mov_b32_e32 v1, 1
	s_waitcnt lgkmcnt(0)
	global_atomic_add v0, v1, s[4:5] offset:1152
.Lwt_1:
	global_load_dword v2, v0, s[4:5] offset:1152 sc1
	s_waitcnt vmcnt(0)
	v_readfirstlane_b32 s8, v2
	s_cmp_ge_u32 s8, s7
	s_cbranch_scc1 .Lac_1
	s_sleep 1
	s_branch .Lwt_1
.Lac_1:
	buffer_inv sc1
	s_waitcnt vmcnt(0)
	s_branch .LBB0_326

; #define LAS __attribute__((address_space(3)))
; __device__ __forceinline__ unsigned xb_ld(unsigned* p)              { return __hip_atomic_load(p, __ATOMIC_RELAXED, __HIP_MEMORY_SCOPE_AGENT); }
; __device__ __forceinline__ unsigned xb_add(unsigned* p, unsigned v) { return __hip_atomic_fetch_add(p, v, __ATOMIC_RELAXED, __HIP_MEMORY_SCOPE_AGENT); }
; __device__ __forceinline__ unsigned xb_xcc_id() { return (unsigned)__builtin_amdgcn_s_getreg((3 << 11) | 20) & 0xFu; }
; #define XB_SPIN(cond, bar) do { unsigned _sp = 0; while (cond) { __builtin_amdgcn_s_sleep(1); \
;     if ((++_sp & 255u) == 0u) { if (xb_ld(&(bar)[XB_TMO])) break; if (_sp > XB_SPIN_CAP) { atomicAdd(&(bar)[XB_TMO], 1u); break; } } } } while (0)
; __device__ __forceinline__ bool is_leader(int wave_s) { int lane; asm volatile("v_mbcnt_lo_u32_b32 %0, -1, 0\n\tv_mbcnt_hi_u32_b32 %0, -1, %0" : "=v"(lane)); return wave_s == 0 && lane == 0; }
; __device__ __forceinline__ void grid_bar(unsigned* bar, volatile LAS unsigned* st, int wave_s, unsigned G) {
;     asm volatile("s_waitcnt vmcnt(0) lgkmcnt(0)" ::: "memory");
;     __syncthreads();
;     if (is_leader(wave_s)) {
;         const unsigned x = xb_xcc_id();
;         unsigned nloc = st[0], nx = st[1];
;         if (nloc == 0u) { xcd_barrier_complete(bar, x, G, nloc, nx); st[0] = nloc; st[1] = nx; }
;         const unsigned old = xb_add(&bar[XB_XSUB(x)], 1u);
;         const unsigned gen = old / nloc;
;         if (old + 1u == (gen + 1u) * nloc) {
;             __builtin_amdgcn_fence(__ATOMIC_RELEASE, "agent");
;             asm volatile("s_waitcnt vmcnt(0)" ::: "memory");
;             const unsigned og = xb_add(&bar[XB_TOP], 1u);
;             const unsigned tg = og / nx;
;             if (og + 1u == (tg + 1u) * nx) xb_add(&bar[XB_TOPGEN], 1u);
;             else XB_SPIN(xb_ld(&bar[XB_TOPGEN]) == tg, bar);
;             __builtin_amdgcn_fence(__ATOMIC_ACQUIRE, "agent");
;             xb_add(&bar[XB_XGEN(x)], 1u);
;             asm volatile("s_waitcnt vmcnt(0)" ::: "memory");
;         } else {
;             XB_SPIN(xb_ld(&bar[XB_XGEN(x)]) == gen, bar);
;             __builtin_amdgcn_fence(__ATOMIC_ACQUIRE, "agent");
;             asm volatile("s_waitcnt vmcnt(0)" ::: "memory");
;         }
;     }
;     __syncthreads();
; }
.LBB0_826:
	s_mov_b32 s2, s94
	s_mov_b32 s4, s95
	s_cmp_lt_i32 s2, 8
	s_cselect_b64 s[2:3], -1, 0
	s_cmp_gt_i32 s4, 7
	s_cselect_b64 s[4:5], -1, 0
	s_and_b64 s[2:3], s[2:3], s[4:5]
	s_andn2_b64 vcc, exec, s[2:3]
	s_cbranch_vccnz .LBB0_881
	s_mov_b32 s2, s94
	s_mov_b32 s4, s95
	s_cmp_lt_i32 s2, 9
	s_cselect_b64 s[2:3], -1, 0
	s_cmp_gt_i32 s4, 8
	s_cselect_b64 s[4:5], -1, 0
	s_and_b64 s[2:3], s[2:3], s[4:5]
	s_andn2_b64 vcc, exec, s[2:3]
	s_cbranch_vccnz .LBB0_881
	s_cmp_lt_u32 s79, 64
	s_waitcnt vmcnt(0) lgkmcnt(0)
	s_cselect_b64 s[2:3], -1, 0
	s_waitcnt vmcnt(0) lgkmcnt(0)
	s_barrier
	v_mbcnt_lo_u32_b32 v0, -1, 0
	v_mbcnt_hi_u32_b32 v0, -1, v0
	s_nop 0
	v_cmp_eq_u32_e32 vcc, 0, v0
	s_and_b64 s[4:5], s[2:3], vcc
	s_and_saveexec_b64 s[2:3], s[4:5]
	s_cbranch_execz .LBB0_880
	s_cmp_eq_u32 s98, 0
	s_cbranch_scc1 .Lgl_2
	s_load_dwordx2 s[4:5], s[0:1], 0xf0
	s_and_b32 s6, s78, 7
	s_lshl_b32 s6, s6, 8
	s_lshr_b32 s7, s92, 3
	s_mul_i32 s7, s7, 2
	v_mov_b32_e32 v0, s6
	v_mov_b32_e32 v1, 1
	s_waitcnt lgkmcnt(0)
	global_atomic_add v0, v1, s[4:5] offset:1152

; #define LAS __attribute__((address_space(3)))
; __device__ __forceinline__ unsigned xb_ld(unsigned* p)              { return __hip_atomic_load(p, __ATOMIC_RELAXED, __HIP_MEMORY_SCOPE_AGENT); }
; __device__ __forceinline__ unsigned xb_add(unsigned* p, unsigned v) { return __hip_atomic_fetch_add(p, v, __ATOMIC_RELAXED, __HIP_MEMORY_SCOPE_AGENT); }
; __device__ __forceinline__ unsigned xb_xcc_id() { return (unsigned)__builtin_amdgcn_s_getreg((3 << 11) | 20) & 0xFu; }
; #define XB_SPIN(cond, bar) do { unsigned _sp = 0; while (cond) { __builtin_amdgcn_s_sleep(1); \
;     if ((++_sp & 255u) == 0u) { if (xb_ld(&(bar)[XB_TMO])) break; if (_sp > XB_SPIN_CAP) { atomicAdd(&(bar)[XB_TMO], 1u); break; } } } } while (0)
; __device__ __forceinline__ bool is_leader(int wave_s) { int lane; asm volatile("v_mbcnt_lo_u32_b32 %0, -1, 0\n\tv_mbcnt_hi_u32_b32 %0, -1, %0" : "=v"(lane)); return wave_s == 0 && lane == 0; }
; __device__ __forceinline__ void grid_bar(unsigned* bar, volatile LAS unsigned* st, int wave_s, unsigned G) {
;     asm volatile("s_waitcnt vmcnt(0) lgkmcnt(0)" ::: "memory");
;     __syncthreads();
;     if (is_leader(wave_s)) {
;         const unsigned x = xb_xcc_id();
;         unsigned nloc = st[0], nx = st[1];
;         if (nloc == 0u) { xcd_barrier_complete(bar, x, G, nloc, nx); st[0] = nloc; st[1] = nx; }
;         const unsigned old = xb_add(&bar[XB_XSUB(x)], 1u);
;         const unsigned gen = old / nloc;
;         if (old + 1u == (gen + 1u) * nloc) {
;             __builtin_amdgcn_fence(__ATOMIC_RELEASE, "agent");
;             asm volatile("s_waitcnt vmcnt(0)" ::: "memory");
;             const unsigned og = xb_add(&bar[XB_TOP], 1u);
;             const unsigned tg = og / nx;
;             if (og + 1u == (tg + 1u) * nx) xb_add(&bar[XB_TOPGEN], 1u);
;             else XB_SPIN(xb_ld(&bar[XB_TOPGEN]) == tg, bar);
;             __builtin_amdgcn_fence(__ATOMIC_ACQUIRE, "agent");
;             xb_add(&bar[XB_XGEN(x)], 1u);
;             asm volatile("s_waitcnt vmcnt(0)" ::: "memory");
;         } else {
;             XB_SPIN(xb_ld(&bar[XB_XGEN(x)]) == gen, bar);
;             __builtin_amdgcn_fence(__ATOMIC_ACQUIRE, "agent");
;             asm volatile("s_waitcnt vmcnt(0)" ::: "memory");
;         }
;     }
;     __syncthreads();
; }
.LBB0_956:
	s_mov_b32 s2, s94
	s_mov_b32 s4, s95
	s_cmp_lt_i32 s2, 9
	s_cselect_b64 s[2:3], -1, 0
	s_cmp_gt_i32 s4, 8
	s_cselect_b64 s[4:5], -1, 0
	s_and_b64 s[2:3], s[2:3], s[4:5]
	s_andn2_b64 vcc, exec, s[2:3]
	s_cbranch_vccnz .LBB0_1011
	s_mov_b32 s2, s94
	s_mov_b32 s4, s95
	s_cmp_lt_i32 s2, 10
	s_cselect_b64 s[2:3], -1, 0
	s_cmp_gt_i32 s4, 9
	s_cselect_b64 s[4:5], -1, 0
	s_and_b64 s[2:3], s[2:3], s[4:5]
	s_andn2_b64 vcc, exec, s[2:3]
	s_cbranch_vccnz .LBB0_1011
	s_cmp_lt_u32 s79, 64
	s_waitcnt vmcnt(0) lgkmcnt(0)
	s_cselect_b64 s[2:3], -1, 0
	s_waitcnt vmcnt(0) lgkmcnt(0)
	s_barrier
	v_mbcnt_lo_u32_b32 v0, -1, 0
	v_mbcnt_hi_u32_b32 v0, -1, v0
	s_nop 0
	v_cmp_eq_u32_e32 vcc, 0, v0
	s_and_b64 s[4:5], s[2:3], vcc
	s_and_saveexec_b64 s[2:3], s[4:5]
	s_cbranch_execz .LBB0_1010
	s_cmp_eq_u32 s98, 0
	s_cbranch_scc1 .Lgl_3
	s_load_dwordx2 s[4:5], s[0:1], 0xf0
	s_and_b32 s6, s78, 7
	s_lshl_b32 s6, s6, 8
	s_lshr_b32 s7, s92, 3
	s_mul_i32 s7, s7, 3
	v_mov_b32_e32 v0, s6
	v_mov_b32_e32 v1, 1
	s_waitcnt lgkmcnt(0)
	global_atomic_add v0, v1, s[4:5] offset:1152

; #define LAS __attribute__((address_space(3)))
; __device__ __forceinline__ unsigned xb_ld(unsigned* p)              { return __hip_atomic_load(p, __ATOMIC_RELAXED, __HIP_MEMORY_SCOPE_AGENT); }
; __device__ __forceinline__ unsigned xb_add(unsigned* p, unsigned v) { return __hip_atomic_fetch_add(p, v, __ATOMIC_RELAXED, __HIP_MEMORY_SCOPE_AGENT); }
; __device__ __forceinline__ unsigned xb_xcc_id() { return (unsigned)__builtin_amdgcn_s_getreg((3 << 11) | 20) & 0xFu; }
; #define XB_SPIN(cond, bar) do { unsigned _sp = 0; while (cond) { __builtin_amdgcn_s_sleep(1); \
;     if ((++_sp & 255u) == 0u) { if (xb_ld(&(bar)[XB_TMO])) break; if (_sp > XB_SPIN_CAP) { atomicAdd(&(bar)[XB_TMO], 1u); break; } } } } while (0)
; __device__ __forceinline__ bool is_leader(int wave_s) { int lane; asm volatile("v_mbcnt_lo_u32_b32 %0, -1, 0\n\tv_mbcnt_hi_u32_b32 %0, -1, %0" : "=v"(lane)); return wave_s == 0 && lane == 0; }
; __device__ __forceinline__ void grid_bar(unsigned* bar, volatile LAS unsigned* st, int wave_s, unsigned G) {
;     asm volatile("s_waitcnt vmcnt(0) lgkmcnt(0)" ::: "memory");
;     __syncthreads();
;     if (is_leader(wave_s)) {
;         const unsigned x = xb_xcc_id();
;         unsigned nloc = st[0], nx = st[1];
;         if (nloc == 0u) { xcd_barrier_complete(bar, x, G, nloc, nx); st[0] = nloc; st[1] = nx; }
;         const unsigned old = xb_add(&bar[XB_XSUB(x)], 1u);
;         const unsigned gen = old / nloc;
;         if (old + 1u == (gen + 1u) * nloc) {
;             __builtin_amdgcn_fence(__ATOMIC_RELEASE, "agent");
;             asm volatile("s_waitcnt vmcnt(0)" ::: "memory");
;             const unsigned og = xb_add(&bar[XB_TOP], 1u);
;             const unsigned tg = og / nx;
;             if (og + 1u == (tg + 1u) * nx) xb_add(&bar[XB_TOPGEN], 1u);
;             else XB_SPIN(xb_ld(&bar[XB_TOPGEN]) == tg, bar);
;             __builtin_amdgcn_fence(__ATOMIC_ACQUIRE, "agent");
;             xb_add(&bar[XB_XGEN(x)], 1u);
;             asm volatile("s_waitcnt vmcnt(0)" ::: "memory");
;         } else {
;             XB_SPIN(xb_ld(&bar[XB_XGEN(x)]) == gen, bar);
;             __builtin_amdgcn_fence(__ATOMIC_ACQUIRE, "agent");
;             asm volatile("s_waitcnt vmcnt(0)" ::: "memory");
;         }
;     }
;     __syncthreads();
; }
.LBB0_1057:
	s_mov_b32 s2, s94
	s_mov_b32 s4, s95
	s_cmp_lt_i32 s2, 10
	s_cselect_b64 s[2:3], -1, 0
	s_cmp_gt_i32 s4, 9
	s_cselect_b64 s[4:5], -1, 0
	s_and_b64 s[2:3], s[2:3], s[4:5]
	s_andn2_b64 vcc, exec, s[2:3]
	s_cbranch_vccnz .LBB0_1112
	s_mov_b32 s2, s94
	s_mov_b32 s4, s95
	s_cmp_lt_i32 s2, 11
	s_cselect_b64 s[2:3], -1, 0
	s_cmp_gt_i32 s4, 10
	s_cselect_b64 s[4:5], -1, 0
	s_and_b64 s[2:3], s[2:3], s[4:5]
	s_andn2_b64 vcc, exec, s[2:3]
	s_cbranch_vccnz .LBB0_1112
	s_cmp_lt_u32 s79, 64
	s_waitcnt vmcnt(0) lgkmcnt(0)
	s_cselect_b64 s[2:3], -1, 0
	s_waitcnt vmcnt(0) lgkmcnt(0)
	s_barrier
	v_mbcnt_lo_u32_b32 v0, -1, 0
	v_mbcnt_hi_u32_b32 v0, -1, v0
	s_nop 0
	v_cmp_eq_u32_e32 vcc, 0, v0
	s_and_b64 s[4:5], s[2:3], vcc
	s_and_saveexec_b64 s[2:3], s[4:5]
	s_cbranch_execz .LBB0_1111
	s_cmp_eq_u32 s98, 0
	s_cbranch_scc1 .Lgl_4
	s_load_dwordx2 s[4:5], s[0:1], 0xf0
	s_and_b32 s6, s78, 7
	s_lshl_b32 s6, s6, 8
	s_lshr_b32 s7, s92, 3
	s_mul_i32 s7, s7, 4
	v_mov_b32_e32 v0, s6
	v_mov_b32_e32 v1, 1
	s_waitcnt lgkmcnt(0)
	global_atomic_add v0, v1, s[4:5] offset:1152

; #define LAS __attribute__((address_space(3)))
; __device__ __forceinline__ unsigned xb_ld(unsigned* p)              { return __hip_atomic_load(p, __ATOMIC_RELAXED, __HIP_MEMORY_SCOPE_AGENT); }
; __device__ __forceinline__ unsigned xb_add(unsigned* p, unsigned v) { return __hip_atomic_fetch_add(p, v, __ATOMIC_RELAXED, __HIP_MEMORY_SCOPE_AGENT); }
; __device__ __forceinline__ unsigned xb_xcc_id() { return (unsigned)__builtin_amdgcn_s_getreg((3 << 11) | 20) & 0xFu; }
; #define XB_SPIN(cond, bar) do { unsigned _sp = 0; while (cond) { __builtin_amdgcn_s_sleep(1); \
;     if ((++_sp & 255u) == 0u) { if (xb_ld(&(bar)[XB_TMO])) break; if (_sp > XB_SPIN_CAP) { atomicAdd(&(bar)[XB_TMO], 1u); break; } } } } while (0)
; __device__ __forceinline__ bool is_leader(int wave_s) { int lane; asm volatile("v_mbcnt_lo_u32_b32 %0, -1, 0\n\tv_mbcnt_hi_u32_b32 %0, -1, %0" : "=v"(lane)); return wave_s == 0 && lane == 0; }
; __device__ __forceinline__ void grid_bar(unsigned* bar, volatile LAS unsigned* st, int wave_s, unsigned G) {
;     asm volatile("s_waitcnt vmcnt(0) lgkmcnt(0)" ::: "memory");
;     __syncthreads();
;     if (is_leader(wave_s)) {
;         const unsigned x = xb_xcc_id();
;         unsigned nloc = st[0], nx = st[1];
;         if (nloc == 0u) { xcd_barrier_complete(bar, x, G, nloc, nx); st[0] = nloc; st[1] = nx; }
;         const unsigned old = xb_add(&bar[XB_XSUB(x)], 1u);
;         const unsigned gen = old / nloc;
;         if (old + 1u == (gen + 1u) * nloc) {
;             __builtin_amdgcn_fence(__ATOMIC_RELEASE, "agent");
;             asm volatile("s_waitcnt vmcnt(0)" ::: "memory");
;             const unsigned og = xb_add(&bar[XB_TOP], 1u);
;             const unsigned tg = og / nx;
;             if (og + 1u == (tg + 1u) * nx) xb_add(&bar[XB_TOPGEN], 1u);
;             else XB_SPIN(xb_ld(&bar[XB_TOPGEN]) == tg, bar);
;             __builtin_amdgcn_fence(__ATOMIC_ACQUIRE, "agent");
;             xb_add(&bar[XB_XGEN(x)], 1u);
;             asm volatile("s_waitcnt vmcnt(0)" ::: "memory");
;         } else {
;             XB_SPIN(xb_ld(&bar[XB_XGEN(x)]) == gen, bar);
;             __builtin_amdgcn_fence(__ATOMIC_ACQUIRE, "agent");
;             asm volatile("s_waitcnt vmcnt(0)" ::: "memory");
;         }
;     }
;     __syncthreads();
; }
.LBB0_1132:
	s_mov_b32 s4, s95
	s_mov_b32 s2, s94
	s_cmp_lt_i32 s2, 11
	s_cselect_b64 s[2:3], -1, 0
	s_cmp_gt_i32 s4, 10
	s_cselect_b64 s[4:5], -1, 0
	s_and_b64 s[2:3], s[2:3], s[4:5]
	s_andn2_b64 vcc, exec, s[2:3]
	s_cbranch_vccnz .LBB0_1187
	s_mov_b32 s4, s95
	s_mov_b32 s2, s94
	s_cmp_lt_i32 s2, 12
	s_cselect_b64 s[2:3], -1, 0
	s_cmp_gt_i32 s4, 11
	s_cselect_b64 s[4:5], -1, 0
	s_and_b64 s[2:3], s[2:3], s[4:5]
	s_andn2_b64 vcc, exec, s[2:3]
	s_cbranch_vccnz .LBB0_1187
	s_cmp_lt_u32 s79, 64
	s_waitcnt vmcnt(0) lgkmcnt(0)
	s_cselect_b64 s[2:3], -1, 0
	s_waitcnt vmcnt(0) lgkmcnt(0)
	s_barrier
	v_mbcnt_lo_u32_b32 v0, -1, 0
	v_mbcnt_hi_u32_b32 v0, -1, v0
	s_nop 0
	v_cmp_eq_u32_e32 vcc, 0, v0
	s_and_b64 s[4:5], s[2:3], vcc
	s_and_saveexec_b64 s[2:3], s[4:5]
	s_cbranch_execz .LBB0_1186
	s_cmp_eq_u32 s98, 0
	s_cbranch_scc1 .Lgl_5
	s_load_dwordx2 s[4:5], s[0:1], 0xf0
	s_and_b32 s6, s78, 7
	s_lshl_b32 s6, s6, 8
	s_lshr_b32 s7, s92, 3
	s_mul_i32 s7, s7, 5
	v_mov_b32_e32 v0, s6
	v_mov_b32_e32 v1, 1
	s_waitcnt lgkmcnt(0)
	global_atomic_add v0, v1, s[4:5] offset:1152

; #define LAS __attribute__((address_space(3)))
; __device__ __forceinline__ unsigned xb_ld(unsigned* p)              { return __hip_atomic_load(p, __ATOMIC_RELAXED, __HIP_MEMORY_SCOPE_AGENT); }
; __device__ __forceinline__ unsigned xb_add(unsigned* p, unsigned v) { return __hip_atomic_fetch_add(p, v, __ATOMIC_RELAXED, __HIP_MEMORY_SCOPE_AGENT); }
; __device__ __forceinline__ unsigned xb_xcc_id() { return (unsigned)__builtin_amdgcn_s_getreg((3 << 11) | 20) & 0xFu; }
; #define XB_SPIN(cond, bar) do { unsigned _sp = 0; while (cond) { __builtin_amdgcn_s_sleep(1); \
;     if ((++_sp & 255u) == 0u) { if (xb_ld(&(bar)[XB_TMO])) break; if (_sp > XB_SPIN_CAP) { atomicAdd(&(bar)[XB_TMO], 1u); break; } } } } while (0)
; __device__ __forceinline__ bool is_leader(int wave_s) { int lane; asm volatile("v_mbcnt_lo_u32_b32 %0, -1, 0\n\tv_mbcnt_hi_u32_b32 %0, -1, %0" : "=v"(lane)); return wave_s == 0 && lane == 0; }
; __device__ __forceinline__ void grid_bar(unsigned* bar, volatile LAS unsigned* st, int wave_s, unsigned G) {
;     asm volatile("s_waitcnt vmcnt(0) lgkmcnt(0)" ::: "memory");
;     __syncthreads();
;     if (is_leader(wave_s)) {
;         const unsigned x = xb_xcc_id();
;         unsigned nloc = st[0], nx = st[1];
;         if (nloc == 0u) { xcd_barrier_complete(bar, x, G, nloc, nx); st[0] = nloc; st[1] = nx; }
;         const unsigned old = xb_add(&bar[XB_XSUB(x)], 1u);
;         const unsigned gen = old / nloc;
;         if (old + 1u == (gen + 1u) * nloc) {
;             __builtin_amdgcn_fence(__ATOMIC_RELEASE, "agent");
;             asm volatile("s_waitcnt vmcnt(0)" ::: "memory");
;             const unsigned og = xb_add(&bar[XB_TOP], 1u);
;             const unsigned tg = og / nx;
;             if (og + 1u == (tg + 1u) * nx) xb_add(&bar[XB_TOPGEN], 1u);
;             else XB_SPIN(xb_ld(&bar[XB_TOPGEN]) == tg, bar);
;             __builtin_amdgcn_fence(__ATOMIC_ACQUIRE, "agent");
;             xb_add(&bar[XB_XGEN(x)], 1u);
;             asm volatile("s_waitcnt vmcnt(0)" ::: "memory");
;         } else {
;             XB_SPIN(xb_ld(&bar[XB_XGEN(x)]) == gen, bar);
;             __builtin_amdgcn_fence(__ATOMIC_ACQUIRE, "agent");
;             asm volatile("s_waitcnt vmcnt(0)" ::: "memory");
;         }
;     }
;     __syncthreads();
; }
.LBB0_1236:
	s_mov_b32 s2, s94
	s_mov_b32 s4, s95
	s_cmp_lt_i32 s2, 12
	s_cselect_b64 s[2:3], -1, 0
	s_cmp_gt_i32 s4, 11
	s_cselect_b64 s[4:5], -1, 0
	s_and_b64 s[2:3], s[2:3], s[4:5]
	s_andn2_b64 vcc, exec, s[2:3]
	s_cbranch_vccnz .LBB0_1291
	s_mov_b32 s2, s94
	s_mov_b32 s4, s95
	s_cmp_lt_i32 s2, 13
	s_cselect_b64 s[2:3], -1, 0
	s_cmp_gt_i32 s4, 12
	s_cselect_b64 s[4:5], -1, 0
	s_and_b64 s[2:3], s[2:3], s[4:5]
	s_andn2_b64 vcc, exec, s[2:3]
	s_cbranch_vccnz .LBB0_1291
	s_cmp_lt_u32 s79, 64
	s_waitcnt vmcnt(0) lgkmcnt(0)
	s_cselect_b64 s[2:3], -1, 0
	s_waitcnt vmcnt(0) lgkmcnt(0)
	s_barrier
	v_mbcnt_lo_u32_b32 v0, -1, 0
	v_mbcnt_hi_u32_b32 v0, -1, v0
	s_nop 0
	v_cmp_eq_u32_e32 vcc, 0, v0
	s_and_b64 s[4:5], s[2:3], vcc
	s_and_saveexec_b64 s[2:3], s[4:5]
	s_cbranch_execz .LBB0_1290
	s_cmp_eq_u32 s98, 0
	s_cbranch_scc1 .Lgl_6
	s_load_dwordx2 s[4:5], s[0:1], 0xf0
	s_and_b32 s6, s78, 7
	s_lshl_b32 s6, s6, 8
	s_lshr_b32 s7, s92, 3
	s_mul_i32 s7, s7, 6
	v_mov_b32_e32 v0, s6
	v_mov_b32_e32 v1, 1
	s_waitcnt lgkmcnt(0)
	global_atomic_add v0, v1, s[4:5] offset:1152

; #define LAS __attribute__((address_space(3)))
; __device__ __forceinline__ unsigned xb_ld(unsigned* p)              { return __hip_atomic_load(p, __ATOMIC_RELAXED, __HIP_MEMORY_SCOPE_AGENT); }
; __device__ __forceinline__ unsigned xb_add(unsigned* p, unsigned v) { return __hip_atomic_fetch_add(p, v, __ATOMIC_RELAXED, __HIP_MEMORY_SCOPE_AGENT); }
; __device__ __forceinline__ unsigned xb_xcc_id() { return (unsigned)__builtin_amdgcn_s_getreg((3 << 11) | 20) & 0xFu; }
; #define XB_SPIN(cond, bar) do { unsigned _sp = 0; while (cond) { __builtin_amdgcn_s_sleep(1); \
;     if ((++_sp & 255u) == 0u) { if (xb_ld(&(bar)[XB_TMO])) break; if (_sp > XB_SPIN_CAP) { atomicAdd(&(bar)[XB_TMO], 1u); break; } } } } while (0)
; __device__ __forceinline__ bool is_leader(int wave_s) { int lane; asm volatile("v_mbcnt_lo_u32_b32 %0, -1, 0\n\tv_mbcnt_hi_u32_b32 %0, -1, %0" : "=v"(lane)); return wave_s == 0 && lane == 0; }
; __device__ __forceinline__ void grid_bar(unsigned* bar, volatile LAS unsigned* st, int wave_s, unsigned G) {
;     asm volatile("s_waitcnt vmcnt(0) lgkmcnt(0)" ::: "memory");
;     __syncthreads();
;     if (is_leader(wave_s)) {
;         const unsigned x = xb_xcc_id();
;         unsigned nloc = st[0], nx = st[1];
;         if (nloc == 0u) { xcd_barrier_complete(bar, x, G, nloc, nx); st[0] = nloc; st[1] = nx; }
;         const unsigned old = xb_add(&bar[XB_XSUB(x)], 1u);
;         const unsigned gen = old / nloc;
;         if (old + 1u == (gen + 1u) * nloc) {
;             __builtin_amdgcn_fence(__ATOMIC_RELEASE, "agent");
;             asm volatile("s_waitcnt vmcnt(0)" ::: "memory");
;             const unsigned og = xb_add(&bar[XB_TOP], 1u);
;             const unsigned tg = og / nx;
;             if (og + 1u == (tg + 1u) * nx) xb_add(&bar[XB_TOPGEN], 1u);
;             else XB_SPIN(xb_ld(&bar[XB_TOPGEN]) == tg, bar);
;             __builtin_amdgcn_fence(__ATOMIC_ACQUIRE, "agent");
;             xb_add(&bar[XB_XGEN(x)], 1u);
;             asm volatile("s_waitcnt vmcnt(0)" ::: "memory");
;         } else {
;             XB_SPIN(xb_ld(&bar[XB_XGEN(x)]) == gen, bar);
;             __builtin_amdgcn_fence(__ATOMIC_ACQUIRE, "agent");
;             asm volatile("s_waitcnt vmcnt(0)" ::: "memory");
;         }
;     }
;     __syncthreads();
; }
.LBB0_1532:
	s_mov_b32 s2, s94
	s_mov_b32 s4, s95
	s_cmp_lt_i32 s2, 15
	s_cselect_b64 s[2:3], -1, 0
	s_cmp_gt_i32 s4, 14
	s_cselect_b64 s[4:5], -1, 0
	s_and_b64 s[2:3], s[2:3], s[4:5]
	s_andn2_b64 vcc, exec, s[2:3]
	s_cbranch_vccnz .LBB0_1587
	s_mov_b32 s2, s94
	s_mov_b32 s4, s95
	s_cmp_lt_i32 s2, 16
	s_cselect_b64 s[2:3], -1, 0
	s_cmp_gt_i32 s4, 15
	s_cselect_b64 s[4:5], -1, 0
	s_and_b64 s[2:3], s[2:3], s[4:5]
	s_andn2_b64 vcc, exec, s[2:3]
	s_cbranch_vccnz .LBB0_1587
	s_cmp_lt_u32 s79, 64
	s_waitcnt vmcnt(0) lgkmcnt(0)
	s_cselect_b64 s[2:3], -1, 0
	s_waitcnt vmcnt(0) lgkmcnt(0)
	s_barrier
	v_mbcnt_lo_u32_b32 v0, -1, 0
	v_mbcnt_hi_u32_b32 v0, -1, v0
	s_nop 0
	v_cmp_eq_u32_e32 vcc, 0, v0
	s_and_b64 s[4:5], s[2:3], vcc
	s_and_saveexec_b64 s[2:3], s[4:5]
	s_cbranch_execz .LBB0_1586
	s_cmp_eq_u32 s98, 0
	s_cbranch_scc1 .Lgl_7
	s_load_dwordx2 s[4:5], s[0:1], 0xf0
	s_and_b32 s6, s78, 7
	s_lshl_b32 s6, s6, 8
	s_lshr_b32 s7, s92, 3
	s_mul_i32 s7, s7, 7
	v_mov_b32_e32 v0, s6
	v_mov_b32_e32 v1, 1
	s_waitcnt lgkmcnt(0)
	global_atomic_add v0, v1, s[4:5] offset:1152

; #define LAS __attribute__((address_space(3)))
; __device__ __forceinline__ unsigned xb_ld(unsigned* p)              { return __hip_atomic_load(p, __ATOMIC_RELAXED, __HIP_MEMORY_SCOPE_AGENT); }
; __device__ __forceinline__ unsigned xb_add(unsigned* p, unsigned v) { return __hip_atomic_fetch_add(p, v, __ATOMIC_RELAXED, __HIP_MEMORY_SCOPE_AGENT); }
; __device__ __forceinline__ unsigned xb_xcc_id() { return (unsigned)__builtin_amdgcn_s_getreg((3 << 11) | 20) & 0xFu; }
; #define XB_SPIN(cond, bar) do { unsigned _sp = 0; while (cond) { __builtin_amdgcn_s_sleep(1); \
;     if ((++_sp & 255u) == 0u) { if (xb_ld(&(bar)[XB_TMO])) break; if (_sp > XB_SPIN_CAP) { atomicAdd(&(bar)[XB_TMO], 1u); break; } } } } while (0)
; __device__ __forceinline__ bool is_leader(int wave_s) { int lane; asm volatile("v_mbcnt_lo_u32_b32 %0, -1, 0\n\tv_mbcnt_hi_u32_b32 %0, -1, %0" : "=v"(lane)); return wave_s == 0 && lane == 0; }
; __device__ __forceinline__ void grid_bar(unsigned* bar, volatile LAS unsigned* st, int wave_s, unsigned G) {
;     asm volatile("s_waitcnt vmcnt(0) lgkmcnt(0)" ::: "memory");
;     __syncthreads();
;     if (is_leader(wave_s)) {
;         const unsigned x = xb_xcc_id();
;         unsigned nloc = st[0], nx = st[1];
;         if (nloc == 0u) { xcd_barrier_complete(bar, x, G, nloc, nx); st[0] = nloc; st[1] = nx; }
;         const unsigned old = xb_add(&bar[XB_XSUB(x)], 1u);
;         const unsigned gen = old / nloc;
;         if (old + 1u == (gen + 1u) * nloc) {
;             __builtin_amdgcn_fence(__ATOMIC_RELEASE, "agent");
;             asm volatile("s_waitcnt vmcnt(0)" ::: "memory");
;             const unsigned og = xb_add(&bar[XB_TOP], 1u);
;             const unsigned tg = og / nx;
;             if (og + 1u == (tg + 1u) * nx) xb_add(&bar[XB_TOPGEN], 1u);
;             else XB_SPIN(xb_ld(&bar[XB_TOPGEN]) == tg, bar);
;             __builtin_amdgcn_fence(__ATOMIC_ACQUIRE, "agent");
;             xb_add(&bar[XB_XGEN(x)], 1u);
;             asm volatile("s_waitcnt vmcnt(0)" ::: "memory");
;         } else {
;             XB_SPIN(xb_ld(&bar[XB_XGEN(x)]) == gen, bar);
;             __builtin_amdgcn_fence(__ATOMIC_ACQUIRE, "agent");
;             asm volatile("s_waitcnt vmcnt(0)" ::: "memory");
;         }
;     }
;     __syncthreads();
; }
.LBB0_1658:
	s_mov_b32 s2, s94
	s_mov_b32 s4, s95
	s_cmp_lt_i32 s2, 17
	s_cselect_b64 s[2:3], -1, 0
	s_cmp_gt_i32 s4, 16
	s_cselect_b64 s[4:5], -1, 0
	s_and_b64 s[2:3], s[2:3], s[4:5]
	s_andn2_b64 vcc, exec, s[2:3]
	s_cbranch_vccnz .LBB0_1713
	s_mov_b32 s2, s94
	s_mov_b32 s4, s95
	s_cmp_lt_i32 s2, 18
	s_cselect_b64 s[2:3], -1, 0
	s_cmp_gt_i32 s4, 17
	s_cselect_b64 s[4:5], -1, 0
	s_and_b64 s[2:3], s[2:3], s[4:5]
	s_andn2_b64 vcc, exec, s[2:3]
	s_cbranch_vccnz .LBB0_1713
	s_cmp_lt_u32 s79, 64
	s_waitcnt vmcnt(0) lgkmcnt(0)
	s_cselect_b64 s[2:3], -1, 0
	s_waitcnt vmcnt(0) lgkmcnt(0)
	s_barrier
	v_mbcnt_lo_u32_b32 v0, -1, 0
	v_mbcnt_hi_u32_b32 v0, -1, v0
	s_nop 0
	v_cmp_eq_u32_e32 vcc, 0, v0
	s_and_b64 s[4:5], s[2:3], vcc
	s_and_saveexec_b64 s[2:3], s[4:5]
	s_cbranch_execz .LBB0_1712
	s_cmp_eq_u32 s98, 0
	s_cbranch_scc1 .Lgl_8
	s_load_dwordx2 s[4:5], s[0:1], 0xf0
	s_and_b32 s6, s78, 7
	s_lshl_b32 s6, s6, 8
	s_lshr_b32 s7, s92, 3
	s_mul_i32 s7, s7, 8
	v_mov_b32_e32 v0, s6
	v_mov_b32_e32 v1, 1
	s_waitcnt lgkmcnt(0)
	global_atomic_add v0, v1, s[4:5] offset:1152

; #define LAS __attribute__((address_space(3)))
; __device__ __forceinline__ unsigned xb_ld(unsigned* p)              { return __hip_atomic_load(p, __ATOMIC_RELAXED, __HIP_MEMORY_SCOPE_AGENT); }
; __device__ __forceinline__ unsigned xb_add(unsigned* p, unsigned v) { return __hip_atomic_fetch_add(p, v, __ATOMIC_RELAXED, __HIP_MEMORY_SCOPE_AGENT); }
; __device__ __forceinline__ unsigned xb_xcc_id() { return (unsigned)__builtin_amdgcn_s_getreg((3 << 11) | 20) & 0xFu; }
; #define XB_SPIN(cond, bar) do { unsigned _sp = 0; while (cond) { __builtin_amdgcn_s_sleep(1); \
;     if ((++_sp & 255u) == 0u) { if (xb_ld(&(bar)[XB_TMO])) break; if (_sp > XB_SPIN_CAP) { atomicAdd(&(bar)[XB_TMO], 1u); break; } } } } while (0)
; __device__ __forceinline__ bool is_leader(int wave_s) { int lane; asm volatile("v_mbcnt_lo_u32_b32 %0, -1, 0\n\tv_mbcnt_hi_u32_b32 %0, -1, %0" : "=v"(lane)); return wave_s == 0 && lane == 0; }
; __device__ __forceinline__ void grid_bar(unsigned* bar, volatile LAS unsigned* st, int wave_s, unsigned G) {
;     asm volatile("s_waitcnt vmcnt(0) lgkmcnt(0)" ::: "memory");
;     __syncthreads();
;     if (is_leader(wave_s)) {
;         const unsigned x = xb_xcc_id();
;         unsigned nloc = st[0], nx = st[1];
;         if (nloc == 0u) { xcd_barrier_complete(bar, x, G, nloc, nx); st[0] = nloc; st[1] = nx; }
;         const unsigned old = xb_add(&bar[XB_XSUB(x)], 1u);
;         const unsigned gen = old / nloc;
;         if (old + 1u == (gen + 1u) * nloc) {
;             __builtin_amdgcn_fence(__ATOMIC_RELEASE, "agent");
;             asm volatile("s_waitcnt vmcnt(0)" ::: "memory");
;             const unsigned og = xb_add(&bar[XB_TOP], 1u);
;             const unsigned tg = og / nx;
;             if (og + 1u == (tg + 1u) * nx) xb_add(&bar[XB_TOPGEN], 1u);
;             else XB_SPIN(xb_ld(&bar[XB_TOPGEN]) == tg, bar);
;             __builtin_amdgcn_fence(__ATOMIC_ACQUIRE, "agent");
;             xb_add(&bar[XB_XGEN(x)], 1u);
;             asm volatile("s_waitcnt vmcnt(0)" ::: "memory");
;         } else {
;             XB_SPIN(xb_ld(&bar[XB_XGEN(x)]) == gen, bar);
;             __builtin_amdgcn_fence(__ATOMIC_ACQUIRE, "agent");
;             asm volatile("s_waitcnt vmcnt(0)" ::: "memory");
;         }
;     }
;     __syncthreads();
; }
.LBB0_1832:
	s_mov_b32 s2, s94
	s_mov_b32 s4, s95
	s_cmp_lt_i32 s2, 19
	s_cselect_b64 s[2:3], -1, 0
	s_cmp_gt_i32 s4, 18
	s_cselect_b64 s[4:5], -1, 0
	s_and_b64 s[2:3], s[2:3], s[4:5]
	s_andn2_b64 vcc, exec, s[2:3]
	s_cbranch_vccnz .LBB0_1887
	s_mov_b32 s2, s94
	s_mov_b32 s4, s95
	s_cmp_lt_i32 s2, 20
	s_cselect_b64 s[2:3], -1, 0
	s_cmp_gt_i32 s4, 19
	s_cselect_b64 s[4:5], -1, 0
	s_and_b64 s[2:3], s[2:3], s[4:5]
	s_andn2_b64 vcc, exec, s[2:3]
	s_cbranch_vccnz .LBB0_1887
	s_cmp_lt_u32 s79, 64
	s_waitcnt vmcnt(0) lgkmcnt(0)
	s_cselect_b64 s[2:3], -1, 0
	s_waitcnt vmcnt(0) lgkmcnt(0)
	s_barrier
	v_mbcnt_lo_u32_b32 v0, -1, 0
	v_mbcnt_hi_u32_b32 v0, -1, v0
	s_nop 0
	v_cmp_eq_u32_e32 vcc, 0, v0
	s_and_b64 s[4:5], s[2:3], vcc
	s_and_saveexec_b64 s[2:3], s[4:5]
	s_cbranch_execz .LBB0_1886
	s_cmp_eq_u32 s98, 0
	s_cbranch_scc1 .Lgl_9
	s_load_dwordx2 s[4:5], s[0:1], 0xf0
	s_and_b32 s6, s78, 7
	s_lshl_b32 s6, s6, 8
	s_lshr_b32 s7, s92, 3
	s_mul_i32 s7, s7, 9
	v_mov_b32_e32 v0, s6
	v_mov_b32_e32 v1, 1
	s_waitcnt lgkmcnt(0)
	global_atomic_add v0, v1, s[4:5] offset:1152

; #define LAS __attribute__((address_space(3)))
; __device__ __forceinline__ unsigned xb_ld(unsigned* p)              { return __hip_atomic_load(p, __ATOMIC_RELAXED, __HIP_MEMORY_SCOPE_AGENT); }
; __device__ __forceinline__ unsigned xb_add(unsigned* p, unsigned v) { return __hip_atomic_fetch_add(p, v, __ATOMIC_RELAXED, __HIP_MEMORY_SCOPE_AGENT); }
; __device__ __forceinline__ unsigned xb_xcc_id() { return (unsigned)__builtin_amdgcn_s_getreg((3 << 11) | 20) & 0xFu; }
; #define XB_SPIN(cond, bar) do { unsigned _sp = 0; while (cond) { __builtin_amdgcn_s_sleep(1); \
;     if ((++_sp & 255u) == 0u) { if (xb_ld(&(bar)[XB_TMO])) break; if (_sp > XB_SPIN_CAP) { atomicAdd(&(bar)[XB_TMO], 1u); break; } } } } while (0)
; __device__ __forceinline__ bool is_leader(int wave_s) { int lane; asm volatile("v_mbcnt_lo_u32_b32 %0, -1, 0\n\tv_mbcnt_hi_u32_b32 %0, -1, %0" : "=v"(lane)); return wave_s == 0 && lane == 0; }
; __device__ __forceinline__ void grid_bar(unsigned* bar, volatile LAS unsigned* st, int wave_s, unsigned G) {
;     asm volatile("s_waitcnt vmcnt(0) lgkmcnt(0)" ::: "memory");
;     __syncthreads();
;     if (is_leader(wave_s)) {
;         const unsigned x = xb_xcc_id();
;         unsigned nloc = st[0], nx = st[1];
;         if (nloc == 0u) { xcd_barrier_complete(bar, x, G, nloc, nx); st[0] = nloc; st[1] = nx; }
;         const unsigned old = xb_add(&bar[XB_XSUB(x)], 1u);
;         const unsigned gen = old / nloc;
;         if (old + 1u == (gen + 1u) * nloc) {
;             __builtin_amdgcn_fence(__ATOMIC_RELEASE, "agent");
;             asm volatile("s_waitcnt vmcnt(0)" ::: "memory");
;             const unsigned og = xb_add(&bar[XB_TOP], 1u);
;             const unsigned tg = og / nx;
;             if (og + 1u == (tg + 1u) * nx) xb_add(&bar[XB_TOPGEN], 1u);
;             else XB_SPIN(xb_ld(&bar[XB_TOPGEN]) == tg, bar);
;             __builtin_amdgcn_fence(__ATOMIC_ACQUIRE, "agent");
;             xb_add(&bar[XB_XGEN(x)], 1u);
;             asm volatile("s_waitcnt vmcnt(0)" ::: "memory");
;         } else {
;             XB_SPIN(xb_ld(&bar[XB_XGEN(x)]) == gen, bar);
;             __builtin_amdgcn_fence(__ATOMIC_ACQUIRE, "agent");
;             asm volatile("s_waitcnt vmcnt(0)" ::: "memory");
;         }
;     }
;     __syncthreads();
; }
.LBB0_1962:
	s_mov_b32 s2, s94
	s_mov_b32 s4, s95
	s_cmp_lt_i32 s2, 20
	s_cselect_b64 s[2:3], -1, 0
	s_cmp_gt_i32 s4, 19
	s_cselect_b64 s[4:5], -1, 0
	s_and_b64 s[2:3], s[2:3], s[4:5]
	s_andn2_b64 vcc, exec, s[2:3]
	s_cbranch_vccnz .LBB0_2017
	s_mov_b32 s2, s94
	s_mov_b32 s4, s95
	s_cmp_lt_i32 s2, 21
	s_cselect_b64 s[2:3], -1, 0
	s_cmp_gt_i32 s4, 20
	s_cselect_b64 s[4:5], -1, 0
	s_and_b64 s[2:3], s[2:3], s[4:5]
	s_andn2_b64 vcc, exec, s[2:3]
	s_cbranch_vccnz .LBB0_2017
	s_cmp_lt_u32 s79, 64
	s_waitcnt vmcnt(0) lgkmcnt(0)
	s_cselect_b64 s[2:3], -1, 0
	s_waitcnt vmcnt(0) lgkmcnt(0)
	s_barrier
	v_mbcnt_lo_u32_b32 v0, -1, 0
	v_mbcnt_hi_u32_b32 v0, -1, v0
	s_nop 0
	v_cmp_eq_u32_e32 vcc, 0, v0
	s_and_b64 s[4:5], s[2:3], vcc
	s_and_saveexec_b64 s[2:3], s[4:5]
	s_cbranch_execz .LBB0_2016
	s_cmp_eq_u32 s98, 0
	s_cbranch_scc1 .Lgl_10
	s_load_dwordx2 s[4:5], s[0:1], 0xf0
	s_and_b32 s6, s78, 7
	s_lshl_b32 s6, s6, 8
	s_lshr_b32 s7, s92, 3
	s_mul_i32 s7, s7, 10
	v_mov_b32_e32 v0, s6
	v_mov_b32_e32 v1, 1
	s_waitcnt lgkmcnt(0)
	global_atomic_add v0, v1, s[4:5] offset:1152
